# speedup vs baseline: 1.0246x; 1.0004x over previous
; __device__ __forceinline__ float bflo(unsigned w) { return __uint_as_float(w << 16); }
; __device__ __forceinline__ float bfhi(unsigned w) { return __uint_as_float(w & 0xffff0000u); }
; template <int MODE, bool PRE = false, bool NEXT = false> ...
;     ...
;       } else if constexpr (MODE == EP_RES) {
;         float* orow = (float*)e.out + (long)row * e.ldo + cbase;
;         const float* arow = (const float*)e.aux + (long)row * e.ldaux + cbase;
;         const u16* brow = (const u16*)e.aux + (long)row * e.ldaux + cbase;
;         u16* xrow = e.xb + (long)row * 1024 + cbase;
;         float part = 0.f;
; #pragma unroll
;         for (int bj = 0; bj < 2; ++bj)
; #pragma unroll
;           for (int n = 0; n < 2; ++n) {
;             f32x4 a;
;             if (e.auxbf) { const u32x2 w = *reinterpret_cast<const u32x2*>(brow + bj * 128 + n * 16); a = f32x4{bflo(w[0]), bfhi(w[0]), bflo(w[1]), bfhi(w[1])}; }
;             else a = *reinterpret_cast<const f32x4*>(arow + bj * 128 + n * 16);
;             a += acc[ai][bj][m][n];
;             if (e.out) *reinterpret_cast<f32x4*>(orow + bj * 128 + n * 16) = a;
;             if (e.xb) {
;               u32x2 w = {cvtpk(a[0], a[1]), cvtpk(a[2], a[3])};
;               *reinterpret_cast<u32x2*>(xrow + bj * 128 + n * 16) = w;
;               part += a[0] * a[0] + a[1] * a[1] + a[2] * a[2] + a[3] * a[3];
;             }
;           }
;         if (e.xb) {
;           part += __int_as_float(__builtin_amdgcn_ds_bpermute((lane ^ 16) << 2, __float_as_int(part)));
;           part += __int_as_float(__builtin_amdgcn_ds_bpermute((lane ^ 32) << 2, __float_as_int(part)));
;           if (fq == 0) reinterpret_cast<float*>(g_lds)[row * 4 + wc] = part;
;         }
.LBB0_969:
	v_readlane_b32 s10, v254, 57
	v_readlane_b32 s11, v254, 58
	v_readfirstlane_b32 s8, v130
	v_mov_b32_e32 v0, 1.0
	s_andn2_b64 vcc, exec, s[10:11]
	s_mov_b32 s59, 0x42b504f3
	s_cbranch_vccnz .LBB0_958
	s_lshl_b64 s[10:11], s[6:7], 19
	v_readlane_b32 s9, v253, 58
	s_add_u32 s9, s9, s10
	v_readlane_b32 s10, v253, 59
	s_addc_u32 s12, s10, s11
	s_lshl_b32 s10, s0, 8
	s_ashr_i32 s11, s10, 31
	s_lshl_b64 s[10:11], s[10:11], 1
	s_add_u32 s10, s9, s10
	s_addc_u32 s11, s12, s11
	s_bfe_u32 s9, s8, 0x20006
	s_ashr_i32 s8, s8, 2
	s_andn2_b32 s8, s8, 63
	v_lshrrev_b32_e32 v0, 1, v130
	v_or_b32_e32 v132, s8, v143
	v_and_b32_e32 v0, 24, v0
	v_lshl_or_b32 v0, s9, 6, v0
	v_ashrrev_i32_e32 v133, 31, v132
	v_lshl_add_u64 v[134:135], s[10:11], 0, v[0:1]
	v_lshlrev_b64 v[136:137], 11, v[132:133]
	v_lshl_add_u64 v[136:137], v[134:135], 0, v[136:137]
	v_mov_b32_e32 v161, 0
	v_mov_b32_e32 v160, v132
	v_lshlrev_b32_e32 v160, 11, v160
	v_lshl_add_u64 v[162:163], v[134:135], 0, v[160:161]
	global_load_dwordx2 v[192:193], v[162:163], off
	global_load_dwordx2 v[194:195], v[162:163], off offset:32
	global_load_dwordx2 v[196:197], v[162:163], off offset:256
	global_load_dwordx2 v[198:199], v[162:163], off offset:288
	v_add_u32_e32 v160, 0x10, v132
	v_lshlrev_b32_e32 v160, 11, v160
	v_lshl_add_u64 v[162:163], v[134:135], 0, v[160:161]
	global_load_dwordx2 v[200:201], v[162:163], off
	global_load_dwordx2 v[202:203], v[162:163], off offset:32
	global_load_dwordx2 v[204:205], v[162:163], off offset:256
	global_load_dwordx2 v[206:207], v[162:163], off offset:288
	v_add_u32_e32 v160, 0x20, v132
	v_lshlrev_b32_e32 v160, 11, v160
	v_lshl_add_u64 v[162:163], v[134:135], 0, v[160:161]
	global_load_dwordx2 v[208:209], v[162:163], off
	global_load_dwordx2 v[210:211], v[162:163], off offset:32
	global_load_dwordx2 v[212:213], v[162:163], off offset:256
	global_load_dwordx2 v[214:215], v[162:163], off offset:288
	v_add_u32_e32 v160, 0x30, v132
	v_lshlrev_b32_e32 v160, 11, v160
	v_lshl_add_u64 v[162:163], v[134:135], 0, v[160:161]
	global_load_dwordx2 v[216:217], v[162:163], off
	global_load_dwordx2 v[218:219], v[162:163], off offset:32
	global_load_dwordx2 v[220:221], v[162:163], off offset:256
	global_load_dwordx2 v[222:223], v[162:163], off offset:288
	v_add_u32_e32 v160, 0x80, v132
	v_lshlrev_b32_e32 v160, 11, v160
	v_lshl_add_u64 v[162:163], v[134:135], 0, v[160:161]
	global_load_dwordx2 v[224:225], v[162:163], off
	global_load_dwordx2 v[226:227], v[162:163], off offset:32
	global_load_dwordx2 v[228:229], v[162:163], off offset:256
	global_load_dwordx2 v[230:231], v[162:163], off offset:288
	v_add_u32_e32 v160, 0x90, v132
	v_lshlrev_b32_e32 v160, 11, v160
	v_lshl_add_u64 v[162:163], v[134:135], 0, v[160:161]
	global_load_dwordx2 v[232:233], v[162:163], off
	global_load_dwordx2 v[234:235], v[162:163], off offset:32
	global_load_dwordx2 v[236:237], v[162:163], off offset:256
	global_load_dwordx2 v[238:239], v[162:163], off offset:288
	v_add_u32_e32 v160, 0xa0, v132
	v_lshlrev_b32_e32 v160, 11, v160
	v_lshl_add_u64 v[162:163], v[134:135], 0, v[160:161]
	global_load_dwordx2 v[240:241], v[162:163], off
	global_load_dwordx2 v[242:243], v[162:163], off offset:32
	global_load_dwordx2 v[244:245], v[162:163], off offset:256
	global_load_dwordx2 v[246:247], v[162:163], off offset:288
	v_add_u32_e32 v160, 0xb0, v132
	v_lshlrev_b32_e32 v160, 11, v160
	v_lshl_add_u64 v[162:163], v[134:135], 0, v[160:161]
	global_load_dwordx2 v[248:249], v[162:163], off
	global_load_dwordx2 v[250:251], v[162:163], off offset:32
	global_load_dwordx2 v[182:183], v[162:163], off offset:256
	global_load_dwordx2 v[184:185], v[162:163], off offset:288
	v_and_b32_e32 v133, 63, v130
	v_lshlrev_b32_e32 v143, 2, v133
	v_xor_b32_e32 v0, 64, v143
	s_lshl_b32 s8, s9, 2
	s_add_i32 s10, s8, 16
	v_cmp_gt_u32_e32 vcc, 16, v133
	s_waitcnt vmcnt(31)
	v_mov_b64_e32 v[138:139], v[192:193]
	v_lshlrev_b32_e32 v140, 16, v138
	v_and_b32_e32 v141, 0xffff0000, v138
	v_lshlrev_b32_e32 v138, 16, v139
	v_and_b32_e32 v139, 0xffff0000, v139
	v_pk_add_f32 v[128:129], v[128:129], v[138:139]
	v_pk_add_f32 v[126:127], v[126:127], v[140:141]
	s_nop 0
	v_cvt_pk_bf16_f32 v138, v126, v127
	v_cvt_pk_bf16_f32 v139, v128, v129
	v_mul_f32_e32 v127, v127, v127
	global_store_dwordx2 v[136:137], v[138:139], off
	v_fmac_f32_e32 v127, v126, v126
	v_fmac_f32_e32 v127, v128, v128
	v_fmac_f32_e32 v127, v129, v129
	s_waitcnt vmcnt(31)
	v_mov_b64_e32 v[140:141], v[194:195]
	v_lshlrev_b32_e32 v138, 16, v140
	v_and_b32_e32 v139, 0xffff0000, v140
	v_lshlrev_b32_e32 v140, 16, v141
	v_and_b32_e32 v141, 0xffff0000, v141
	v_pk_add_f32 v[124:125], v[124:125], v[140:141]
	v_pk_add_f32 v[122:123], v[122:123], v[138:139]
	s_nop 0
	v_cvt_pk_bf16_f32 v138, v122, v123
	v_cvt_pk_bf16_f32 v139, v124, v125
	v_mul_f32_e32 v123, v123, v123
	global_store_dwordx2 v[136:137], v[138:139], off offset:32
	v_fmac_f32_e32 v123, v122, v122
	v_fmac_f32_e32 v123, v124, v124
	v_fmac_f32_e32 v123, v125, v125
	v_add_f32_e32 v122, v127, v123
	s_waitcnt vmcnt(31)
	v_mov_b64_e32 v[140:141], v[196:197]
	v_lshlrev_b32_e32 v138, 16, v140
	v_and_b32_e32 v139, 0xffff0000, v140
	v_lshlrev_b32_e32 v140, 16, v141
	v_and_b32_e32 v141, 0xffff0000, v141
	v_pk_add_f32 v[120:121], v[120:121], v[140:141]
	v_pk_add_f32 v[118:119], v[118:119], v[138:139]
	s_nop 0
	v_cvt_pk_bf16_f32 v138, v118, v119
	v_cvt_pk_bf16_f32 v139, v120, v121
	v_mul_f32_e32 v119, v119, v119
	v_fmac_f32_e32 v119, v118, v118
	v_fmac_f32_e32 v119, v120, v120
	v_fmac_f32_e32 v119, v121, v121
	v_add_f32_e32 v122, v122, v119
	global_store_dwordx2 v[136:137], v[138:139], off offset:256
	s_waitcnt vmcnt(31)
	v_mov_b64_e32 v[140:141], v[198:199]
	v_lshlrev_b32_e32 v118, 16, v140
	v_and_b32_e32 v119, 0xffff0000, v140
	v_pk_add_f32 v[118:119], v[114:115], v[118:119]
	v_lshlrev_b32_e32 v120, 16, v141
	v_and_b32_e32 v121, 0xffff0000, v141
	v_mul_f32_e32 v114, v119, v119
	v_pk_add_f32 v[120:121], v[116:117], v[120:121]
	v_fmac_f32_e32 v114, v118, v118
	v_fmac_f32_e32 v114, v120, v120
	v_fmac_f32_e32 v114, v121, v121
	v_add_f32_e32 v114, v122, v114
	ds_bpermute_b32 v115, v0, v114
	v_xor_b32_e32 v116, 0x80, v143
	v_cvt_pk_bf16_f32 v118, v118, v119
	v_cvt_pk_bf16_f32 v119, v120, v121
	global_store_dwordx2 v[136:137], v[118:119], off offset:288
	s_waitcnt lgkmcnt(0)
	v_add_f32_e32 v114, v114, v115
	ds_bpermute_b32 v115, v116, v114
	s_and_saveexec_b64 s[8:9], vcc
	s_cbranch_execz .LBB0_972
	s_waitcnt lgkmcnt(0)
	v_add_f32_e32 v114, v114, v115
	v_lshl_add_u32 v115, v132, 4, s10
	ds_write_b32 v115, v114
; __device__ __forceinline__ float bflo(unsigned w) { return __uint_as_float(w << 16); }
; __device__ __forceinline__ float bfhi(unsigned w) { return __uint_as_float(w & 0xffff0000u); }
; template <int MODE, bool PRE = false, bool NEXT = false> ...
;     ...
;       } else if constexpr (MODE == EP_RES) {
;         float* orow = (float*)e.out + (long)row * e.ldo + cbase;
;         const float* arow = (const float*)e.aux + (long)row * e.ldaux + cbase;
;         const u16* brow = (const u16*)e.aux + (long)row * e.ldaux + cbase;
;         u16* xrow = e.xb + (long)row * 1024 + cbase;
;         float part = 0.f;
; #pragma unroll
;         for (int bj = 0; bj < 2; ++bj)
; #pragma unroll
;           for (int n = 0; n < 2; ++n) {
;             f32x4 a;
;             if (e.auxbf) { const u32x2 w = *reinterpret_cast<const u32x2*>(brow + bj * 128 + n * 16); a = f32x4{bflo(w[0]), bfhi(w[0]), bflo(w[1]), bfhi(w[1])}; }
;             else a = *reinterpret_cast<const f32x4*>(arow + bj * 128 + n * 16);
;             a += acc[ai][bj][m][n];
;             if (e.out) *reinterpret_cast<f32x4*>(orow + bj * 128 + n * 16) = a;
;             if (e.xb) {
;               u32x2 w = {cvtpk(a[0], a[1]), cvtpk(a[2], a[3])};
;               *reinterpret_cast<u32x2*>(xrow + bj * 128 + n * 16) = w;
;               part += a[0] * a[0] + a[1] * a[1] + a[2] * a[2] + a[3] * a[3];
;             }
;           }
;         if (e.xb) {
;           part += __int_as_float(__builtin_amdgcn_ds_bpermute((lane ^ 16) << 2, __float_as_int(part)));
;           part += __int_as_float(__builtin_amdgcn_ds_bpermute((lane ^ 32) << 2, __float_as_int(part)));
;           if (fq == 0) reinterpret_cast<float*>(g_lds)[row * 4 + wc] = part;
;         }
.LBB0_972:
	s_or_b64 exec, exec, s[8:9]
	v_or_b32_e32 v114, 16, v132
	s_waitcnt lgkmcnt(0)
	v_ashrrev_i32_e32 v115, 31, v114
	v_lshlrev_b64 v[118:119], 11, v[114:115]
	v_lshl_add_u64 v[118:119], v[134:135], 0, v[118:119]
	s_waitcnt vmcnt(31)
	v_mov_b64_e32 v[120:121], v[200:201]
	v_lshlrev_b32_e32 v122, 16, v120
	v_and_b32_e32 v123, 0xffff0000, v120
	v_lshlrev_b32_e32 v120, 16, v121
	v_and_b32_e32 v121, 0xffff0000, v121
	v_pk_add_f32 v[112:113], v[112:113], v[120:121]
	v_pk_add_f32 v[110:111], v[110:111], v[122:123]
	s_nop 0
	v_cvt_pk_bf16_f32 v120, v110, v111
	v_cvt_pk_bf16_f32 v121, v112, v113
	v_mul_f32_e32 v111, v111, v111
	global_store_dwordx2 v[118:119], v[120:121], off
	v_fmac_f32_e32 v111, v110, v110
	v_fmac_f32_e32 v111, v112, v112
	v_fmac_f32_e32 v111, v113, v113
	s_waitcnt vmcnt(31)
	v_mov_b64_e32 v[122:123], v[202:203]
	v_lshlrev_b32_e32 v120, 16, v122
	v_and_b32_e32 v121, 0xffff0000, v122
	v_lshlrev_b32_e32 v122, 16, v123
	v_and_b32_e32 v123, 0xffff0000, v123
	v_pk_add_f32 v[108:109], v[108:109], v[122:123]
	v_pk_add_f32 v[106:107], v[106:107], v[120:121]
	s_nop 0
	v_cvt_pk_bf16_f32 v120, v106, v107
	v_cvt_pk_bf16_f32 v121, v108, v109
	v_mul_f32_e32 v107, v107, v107
	global_store_dwordx2 v[118:119], v[120:121], off offset:32
	v_fmac_f32_e32 v107, v106, v106
	v_fmac_f32_e32 v107, v108, v108
	v_fmac_f32_e32 v107, v109, v109
	v_add_f32_e32 v106, v111, v107
	s_waitcnt vmcnt(31)
	v_mov_b64_e32 v[122:123], v[204:205]
	v_lshlrev_b32_e32 v120, 16, v122
	v_and_b32_e32 v121, 0xffff0000, v122
	v_lshlrev_b32_e32 v122, 16, v123
	v_and_b32_e32 v123, 0xffff0000, v123
	v_pk_add_f32 v[104:105], v[104:105], v[122:123]
	v_pk_add_f32 v[102:103], v[102:103], v[120:121]
	s_nop 0
	v_cvt_pk_bf16_f32 v120, v102, v103
	v_cvt_pk_bf16_f32 v121, v104, v105
	v_mul_f32_e32 v103, v103, v103
	v_fmac_f32_e32 v103, v102, v102
	v_fmac_f32_e32 v103, v104, v104
	v_fmac_f32_e32 v103, v105, v105
	v_add_f32_e32 v106, v106, v103
	global_store_dwordx2 v[118:119], v[120:121], off offset:256
	s_waitcnt vmcnt(31)
	v_mov_b64_e32 v[122:123], v[206:207]
	v_lshlrev_b32_e32 v102, 16, v122
	v_and_b32_e32 v103, 0xffff0000, v122
	v_pk_add_f32 v[102:103], v[98:99], v[102:103]
	v_lshlrev_b32_e32 v104, 16, v123
	v_and_b32_e32 v105, 0xffff0000, v123
	v_mul_f32_e32 v98, v103, v103
	v_pk_add_f32 v[100:101], v[100:101], v[104:105]
	v_fmac_f32_e32 v98, v102, v102
	v_fmac_f32_e32 v98, v100, v100
	v_fmac_f32_e32 v98, v101, v101
	v_add_f32_e32 v98, v106, v98
	ds_bpermute_b32 v99, v0, v98
	v_cvt_pk_bf16_f32 v102, v102, v103
	v_cvt_pk_bf16_f32 v103, v100, v101
	global_store_dwordx2 v[118:119], v[102:103], off offset:288
	s_waitcnt lgkmcnt(0)
	v_add_f32_e32 v98, v98, v99
	ds_bpermute_b32 v99, v116, v98
	s_and_saveexec_b64 s[8:9], vcc
	s_cbranch_execz .LBB0_974
	s_waitcnt lgkmcnt(0)
	v_add_f32_e32 v98, v98, v99
	v_lshl_add_u32 v99, v114, 4, s10
	ds_write_b32 v99, v98
.LBB0_974:
	s_or_b64 exec, exec, s[8:9]
	v_or_b32_e32 v98, 32, v132
	s_waitcnt lgkmcnt(0)
	v_ashrrev_i32_e32 v99, 31, v98
	v_lshlrev_b64 v[100:101], 11, v[98:99]
	v_lshl_add_u64 v[100:101], v[134:135], 0, v[100:101]
	s_waitcnt vmcnt(31)
	v_mov_b64_e32 v[102:103], v[208:209]
	v_lshlrev_b32_e32 v104, 16, v102
	v_and_b32_e32 v105, 0xffff0000, v102
	v_lshlrev_b32_e32 v102, 16, v103
	v_and_b32_e32 v103, 0xffff0000, v103
	v_pk_add_f32 v[96:97], v[96:97], v[102:103]
	v_pk_add_f32 v[94:95], v[94:95], v[104:105]
	s_nop 0
	v_cvt_pk_bf16_f32 v102, v94, v95
	v_cvt_pk_bf16_f32 v103, v96, v97
	v_mul_f32_e32 v95, v95, v95
	global_store_dwordx2 v[100:101], v[102:103], off
	v_fmac_f32_e32 v95, v94, v94
	v_fmac_f32_e32 v95, v96, v96
	v_fmac_f32_e32 v95, v97, v97
	s_waitcnt vmcnt(31)
	v_mov_b64_e32 v[104:105], v[210:211]
	v_lshlrev_b32_e32 v102, 16, v104
	v_and_b32_e32 v103, 0xffff0000, v104
	v_lshlrev_b32_e32 v104, 16, v105
	v_and_b32_e32 v105, 0xffff0000, v105
	v_pk_add_f32 v[92:93], v[92:93], v[104:105]
	v_pk_add_f32 v[90:91], v[90:91], v[102:103]
	s_nop 0
	v_cvt_pk_bf16_f32 v102, v90, v91
	v_cvt_pk_bf16_f32 v103, v92, v93
	v_mul_f32_e32 v91, v91, v91
	global_store_dwordx2 v[100:101], v[102:103], off offset:32
	v_fmac_f32_e32 v91, v90, v90
	v_fmac_f32_e32 v91, v92, v92
	v_fmac_f32_e32 v91, v93, v93
	v_add_f32_e32 v90, v95, v91
	s_waitcnt vmcnt(31)
	v_mov_b64_e32 v[104:105], v[212:213]
	v_lshlrev_b32_e32 v102, 16, v104
	v_and_b32_e32 v103, 0xffff0000, v104
	v_lshlrev_b32_e32 v104, 16, v105
	v_and_b32_e32 v105, 0xffff0000, v105
	v_pk_add_f32 v[88:89], v[88:89], v[104:105]
	v_pk_add_f32 v[86:87], v[86:87], v[102:103]
	s_nop 0
	v_cvt_pk_bf16_f32 v102, v86, v87
	v_cvt_pk_bf16_f32 v103, v88, v89
	v_mul_f32_e32 v87, v87, v87
	v_fmac_f32_e32 v87, v86, v86
	v_fmac_f32_e32 v87, v88, v88
	v_fmac_f32_e32 v87, v89, v89
	v_add_f32_e32 v90, v90, v87
	global_store_dwordx2 v[100:101], v[102:103], off offset:256
	s_waitcnt vmcnt(31)
	v_mov_b64_e32 v[104:105], v[214:215]
	v_lshlrev_b32_e32 v86, 16, v104
	v_and_b32_e32 v87, 0xffff0000, v104
	v_pk_add_f32 v[86:87], v[82:83], v[86:87]
	v_lshlrev_b32_e32 v88, 16, v105
	v_and_b32_e32 v89, 0xffff0000, v105
	v_mul_f32_e32 v82, v87, v87
	v_pk_add_f32 v[84:85], v[84:85], v[88:89]
	v_fmac_f32_e32 v82, v86, v86
	v_fmac_f32_e32 v82, v84, v84
	v_fmac_f32_e32 v82, v85, v85
	v_add_f32_e32 v82, v90, v82
	ds_bpermute_b32 v83, v0, v82
	v_cvt_pk_bf16_f32 v86, v86, v87
	v_cvt_pk_bf16_f32 v87, v84, v85
	global_store_dwordx2 v[100:101], v[86:87], off offset:288
	s_waitcnt lgkmcnt(0)
	v_add_f32_e32 v82, v82, v83
	ds_bpermute_b32 v83, v116, v82
	s_and_saveexec_b64 s[8:9], vcc
	s_cbranch_execz .LBB0_976
	s_waitcnt lgkmcnt(0)
	v_add_f32_e32 v82, v82, v83
	v_lshl_add_u32 v83, v98, 4, s10
	ds_write_b32 v83, v82
; __device__ __forceinline__ float bflo(unsigned w) { return __uint_as_float(w << 16); }
; __device__ __forceinline__ float bfhi(unsigned w) { return __uint_as_float(w & 0xffff0000u); }
; template <int MODE, bool PRE = false, bool NEXT = false> ...
;     ...
;       } else if constexpr (MODE == EP_RES) {
;         float* orow = (float*)e.out + (long)row * e.ldo + cbase;
;         const float* arow = (const float*)e.aux + (long)row * e.ldaux + cbase;
;         const u16* brow = (const u16*)e.aux + (long)row * e.ldaux + cbase;
;         u16* xrow = e.xb + (long)row * 1024 + cbase;
;         float part = 0.f;
; #pragma unroll
;         for (int bj = 0; bj < 2; ++bj)
; #pragma unroll
;           for (int n = 0; n < 2; ++n) {
;             f32x4 a;
;             if (e.auxbf) { const u32x2 w = *reinterpret_cast<const u32x2*>(brow + bj * 128 + n * 16); a = f32x4{bflo(w[0]), bfhi(w[0]), bflo(w[1]), bfhi(w[1])}; }
;             else a = *reinterpret_cast<const f32x4*>(arow + bj * 128 + n * 16);
;             a += acc[ai][bj][m][n];
;             if (e.out) *reinterpret_cast<f32x4*>(orow + bj * 128 + n * 16) = a;
;             if (e.xb) {
;               u32x2 w = {cvtpk(a[0], a[1]), cvtpk(a[2], a[3])};
;               *reinterpret_cast<u32x2*>(xrow + bj * 128 + n * 16) = w;
;               part += a[0] * a[0] + a[1] * a[1] + a[2] * a[2] + a[3] * a[3];
;             }
;           }
;         if (e.xb) {
;           part += __int_as_float(__builtin_amdgcn_ds_bpermute((lane ^ 16) << 2, __float_as_int(part)));
;           part += __int_as_float(__builtin_amdgcn_ds_bpermute((lane ^ 32) << 2, __float_as_int(part)));
;           if (fq == 0) reinterpret_cast<float*>(g_lds)[row * 4 + wc] = part;
;         }
.LBB0_976:
	s_or_b64 exec, exec, s[8:9]
	v_or_b32_e32 v82, 48, v132
	s_waitcnt lgkmcnt(0)
	v_ashrrev_i32_e32 v83, 31, v82
	v_lshlrev_b64 v[84:85], 11, v[82:83]
	v_lshl_add_u64 v[84:85], v[134:135], 0, v[84:85]
	s_waitcnt vmcnt(31)
	v_mov_b64_e32 v[86:87], v[216:217]
	v_lshlrev_b32_e32 v88, 16, v86
	v_and_b32_e32 v89, 0xffff0000, v86
	v_lshlrev_b32_e32 v86, 16, v87
	v_and_b32_e32 v87, 0xffff0000, v87
	v_pk_add_f32 v[80:81], v[80:81], v[86:87]
	v_pk_add_f32 v[78:79], v[78:79], v[88:89]
	s_nop 0
	v_cvt_pk_bf16_f32 v86, v78, v79
	v_cvt_pk_bf16_f32 v87, v80, v81
	v_mul_f32_e32 v79, v79, v79
	global_store_dwordx2 v[84:85], v[86:87], off
	v_fmac_f32_e32 v79, v78, v78
	v_fmac_f32_e32 v79, v80, v80
	v_fmac_f32_e32 v79, v81, v81
	s_waitcnt vmcnt(31)
	v_mov_b64_e32 v[88:89], v[218:219]
	v_lshlrev_b32_e32 v86, 16, v88
	v_and_b32_e32 v87, 0xffff0000, v88
	v_lshlrev_b32_e32 v88, 16, v89
	v_and_b32_e32 v89, 0xffff0000, v89
	v_pk_add_f32 v[76:77], v[76:77], v[88:89]
	v_pk_add_f32 v[74:75], v[74:75], v[86:87]
	s_nop 0
	v_cvt_pk_bf16_f32 v86, v74, v75
	v_cvt_pk_bf16_f32 v87, v76, v77
	v_mul_f32_e32 v75, v75, v75
	global_store_dwordx2 v[84:85], v[86:87], off offset:32
	v_fmac_f32_e32 v75, v74, v74
	v_fmac_f32_e32 v75, v76, v76
	v_fmac_f32_e32 v75, v77, v77
	v_add_f32_e32 v74, v79, v75
	s_waitcnt vmcnt(31)
	v_mov_b64_e32 v[88:89], v[220:221]
	v_lshlrev_b32_e32 v86, 16, v88
	v_and_b32_e32 v87, 0xffff0000, v88
	v_lshlrev_b32_e32 v88, 16, v89
	v_and_b32_e32 v89, 0xffff0000, v89
	v_pk_add_f32 v[72:73], v[72:73], v[88:89]
	v_pk_add_f32 v[70:71], v[70:71], v[86:87]
	s_nop 0
	v_cvt_pk_bf16_f32 v86, v70, v71
	v_cvt_pk_bf16_f32 v87, v72, v73
	v_mul_f32_e32 v71, v71, v71
	v_fmac_f32_e32 v71, v70, v70
	v_fmac_f32_e32 v71, v72, v72
	v_fmac_f32_e32 v71, v73, v73
	v_add_f32_e32 v74, v74, v71
	global_store_dwordx2 v[84:85], v[86:87], off offset:256
	s_waitcnt vmcnt(31)
	v_mov_b64_e32 v[88:89], v[222:223]
	v_lshlrev_b32_e32 v70, 16, v88
	v_and_b32_e32 v71, 0xffff0000, v88
	v_pk_add_f32 v[70:71], v[66:67], v[70:71]
	v_lshlrev_b32_e32 v72, 16, v89
	v_and_b32_e32 v73, 0xffff0000, v89
	v_mul_f32_e32 v66, v71, v71
	v_pk_add_f32 v[68:69], v[68:69], v[72:73]
	v_fmac_f32_e32 v66, v70, v70
	v_fmac_f32_e32 v66, v68, v68
	v_fmac_f32_e32 v66, v69, v69
	v_add_f32_e32 v66, v74, v66
	ds_bpermute_b32 v67, v0, v66
	v_cvt_pk_bf16_f32 v70, v70, v71
	v_cvt_pk_bf16_f32 v71, v68, v69
	global_store_dwordx2 v[84:85], v[70:71], off offset:288
	s_waitcnt lgkmcnt(0)
	v_add_f32_e32 v66, v66, v67
	ds_bpermute_b32 v67, v116, v66
	s_and_saveexec_b64 s[8:9], vcc
	s_cbranch_execz .LBB0_978
	s_waitcnt lgkmcnt(0)
	v_add_f32_e32 v66, v66, v67
	v_lshl_add_u32 v67, v82, 4, s10
	ds_write_b32 v67, v66
.LBB0_978:
	s_or_b64 exec, exec, s[8:9]
	v_add_u32_e32 v66, 0x80, v132
	s_waitcnt lgkmcnt(0)
	v_ashrrev_i32_e32 v67, 31, v66
	v_lshlrev_b64 v[68:69], 11, v[66:67]
	v_lshl_add_u64 v[68:69], v[134:135], 0, v[68:69]
	s_waitcnt vmcnt(31)
	v_mov_b64_e32 v[70:71], v[224:225]
	v_lshlrev_b32_e32 v72, 16, v70
	v_and_b32_e32 v73, 0xffff0000, v70
	v_lshlrev_b32_e32 v70, 16, v71
	v_and_b32_e32 v71, 0xffff0000, v71
	v_pk_add_f32 v[64:65], v[64:65], v[70:71]
	v_pk_add_f32 v[62:63], v[62:63], v[72:73]
	s_nop 0
	v_cvt_pk_bf16_f32 v70, v62, v63
	v_cvt_pk_bf16_f32 v71, v64, v65
	v_mul_f32_e32 v63, v63, v63
	global_store_dwordx2 v[68:69], v[70:71], off
	v_fmac_f32_e32 v63, v62, v62
	v_fmac_f32_e32 v63, v64, v64
	v_fmac_f32_e32 v63, v65, v65
	s_waitcnt vmcnt(31)
	v_mov_b64_e32 v[72:73], v[226:227]
	v_lshlrev_b32_e32 v70, 16, v72
	v_and_b32_e32 v71, 0xffff0000, v72
	v_lshlrev_b32_e32 v72, 16, v73
	v_and_b32_e32 v73, 0xffff0000, v73
	v_pk_add_f32 v[60:61], v[60:61], v[72:73]
	v_pk_add_f32 v[58:59], v[58:59], v[70:71]
	s_nop 0
	v_cvt_pk_bf16_f32 v70, v58, v59
	v_cvt_pk_bf16_f32 v71, v60, v61
	v_mul_f32_e32 v59, v59, v59
	global_store_dwordx2 v[68:69], v[70:71], off offset:32
	v_fmac_f32_e32 v59, v58, v58
	v_fmac_f32_e32 v59, v60, v60
	v_fmac_f32_e32 v59, v61, v61
	v_add_f32_e32 v58, v63, v59
	s_waitcnt vmcnt(31)
	v_mov_b64_e32 v[72:73], v[228:229]
	v_lshlrev_b32_e32 v70, 16, v72
	v_and_b32_e32 v71, 0xffff0000, v72
	v_lshlrev_b32_e32 v72, 16, v73
	v_and_b32_e32 v73, 0xffff0000, v73
	v_pk_add_f32 v[56:57], v[56:57], v[72:73]
	v_pk_add_f32 v[54:55], v[54:55], v[70:71]
	s_nop 0
	v_cvt_pk_bf16_f32 v70, v54, v55
	v_cvt_pk_bf16_f32 v71, v56, v57
	v_mul_f32_e32 v55, v55, v55
	v_fmac_f32_e32 v55, v54, v54
	v_fmac_f32_e32 v55, v56, v56
	v_fmac_f32_e32 v55, v57, v57
	v_add_f32_e32 v58, v58, v55
	global_store_dwordx2 v[68:69], v[70:71], off offset:256
	s_waitcnt vmcnt(31)
	v_mov_b64_e32 v[72:73], v[230:231]
	v_lshlrev_b32_e32 v54, 16, v72
	v_and_b32_e32 v55, 0xffff0000, v72
	v_pk_add_f32 v[54:55], v[50:51], v[54:55]
	v_lshlrev_b32_e32 v56, 16, v73
	v_and_b32_e32 v57, 0xffff0000, v73
	v_mul_f32_e32 v50, v55, v55
	v_pk_add_f32 v[52:53], v[52:53], v[56:57]
	v_fmac_f32_e32 v50, v54, v54
	v_fmac_f32_e32 v50, v52, v52
	v_fmac_f32_e32 v50, v53, v53
	v_add_f32_e32 v50, v58, v50
	ds_bpermute_b32 v51, v0, v50
	v_cvt_pk_bf16_f32 v54, v54, v55
	v_cvt_pk_bf16_f32 v55, v52, v53
	global_store_dwordx2 v[68:69], v[54:55], off offset:288
	s_waitcnt lgkmcnt(0)
	v_add_f32_e32 v50, v50, v51
	ds_bpermute_b32 v51, v116, v50
	s_and_saveexec_b64 s[8:9], vcc
	s_cbranch_execz .LBB0_980
	s_waitcnt lgkmcnt(0)
	v_add_f32_e32 v50, v50, v51
	v_lshl_add_u32 v51, v66, 4, s10
	ds_write_b32 v51, v50
; __device__ __forceinline__ float bflo(unsigned w) { return __uint_as_float(w << 16); }
; __device__ __forceinline__ float bfhi(unsigned w) { return __uint_as_float(w & 0xffff0000u); }
; template <int MODE, bool PRE = false, bool NEXT = false> ...
;     ...
;       } else if constexpr (MODE == EP_RES) {
;         float* orow = (float*)e.out + (long)row * e.ldo + cbase;
;         const float* arow = (const float*)e.aux + (long)row * e.ldaux + cbase;
;         const u16* brow = (const u16*)e.aux + (long)row * e.ldaux + cbase;
;         u16* xrow = e.xb + (long)row * 1024 + cbase;
;         float part = 0.f;
; #pragma unroll
;         for (int bj = 0; bj < 2; ++bj)
; #pragma unroll
;           for (int n = 0; n < 2; ++n) {
;             f32x4 a;
;             if (e.auxbf) { const u32x2 w = *reinterpret_cast<const u32x2*>(brow + bj * 128 + n * 16); a = f32x4{bflo(w[0]), bfhi(w[0]), bflo(w[1]), bfhi(w[1])}; }
;             else a = *reinterpret_cast<const f32x4*>(arow + bj * 128 + n * 16);
;             a += acc[ai][bj][m][n];
;             if (e.out) *reinterpret_cast<f32x4*>(orow + bj * 128 + n * 16) = a;
;             if (e.xb) {
;               u32x2 w = {cvtpk(a[0], a[1]), cvtpk(a[2], a[3])};
;               *reinterpret_cast<u32x2*>(xrow + bj * 128 + n * 16) = w;
;               part += a[0] * a[0] + a[1] * a[1] + a[2] * a[2] + a[3] * a[3];
;             }
;           }
;         if (e.xb) {
;           part += __int_as_float(__builtin_amdgcn_ds_bpermute((lane ^ 16) << 2, __float_as_int(part)));
;           part += __int_as_float(__builtin_amdgcn_ds_bpermute((lane ^ 32) << 2, __float_as_int(part)));
;           if (fq == 0) reinterpret_cast<float*>(g_lds)[row * 4 + wc] = part;
;         }
.LBB0_980:
	s_or_b64 exec, exec, s[8:9]
	v_add_u32_e32 v50, 0x90, v132
	s_waitcnt lgkmcnt(0)
	v_ashrrev_i32_e32 v51, 31, v50
	v_lshlrev_b64 v[52:53], 11, v[50:51]
	v_lshl_add_u64 v[52:53], v[134:135], 0, v[52:53]
	s_waitcnt vmcnt(31)
	v_mov_b64_e32 v[54:55], v[232:233]
	v_lshlrev_b32_e32 v56, 16, v54
	v_and_b32_e32 v57, 0xffff0000, v54
	v_lshlrev_b32_e32 v54, 16, v55
	v_and_b32_e32 v55, 0xffff0000, v55
	v_pk_add_f32 v[48:49], v[48:49], v[54:55]
	v_pk_add_f32 v[46:47], v[46:47], v[56:57]
	s_nop 0
	v_cvt_pk_bf16_f32 v54, v46, v47
	v_cvt_pk_bf16_f32 v55, v48, v49
	v_mul_f32_e32 v47, v47, v47
	global_store_dwordx2 v[52:53], v[54:55], off
	v_fmac_f32_e32 v47, v46, v46
	v_fmac_f32_e32 v47, v48, v48
	v_fmac_f32_e32 v47, v49, v49
	s_waitcnt vmcnt(31)
	v_mov_b64_e32 v[56:57], v[234:235]
	v_lshlrev_b32_e32 v54, 16, v56
	v_and_b32_e32 v55, 0xffff0000, v56
	v_lshlrev_b32_e32 v56, 16, v57
	v_and_b32_e32 v57, 0xffff0000, v57
	v_pk_add_f32 v[44:45], v[44:45], v[56:57]
	v_pk_add_f32 v[42:43], v[42:43], v[54:55]
	s_nop 0
	v_cvt_pk_bf16_f32 v54, v42, v43
	v_cvt_pk_bf16_f32 v55, v44, v45
	v_mul_f32_e32 v43, v43, v43
	global_store_dwordx2 v[52:53], v[54:55], off offset:32
	v_fmac_f32_e32 v43, v42, v42
	v_fmac_f32_e32 v43, v44, v44
	v_fmac_f32_e32 v43, v45, v45
	v_add_f32_e32 v42, v47, v43
	s_waitcnt vmcnt(31)
	v_mov_b64_e32 v[56:57], v[236:237]
	v_lshlrev_b32_e32 v54, 16, v56
	v_and_b32_e32 v55, 0xffff0000, v56
	v_lshlrev_b32_e32 v56, 16, v57
	v_and_b32_e32 v57, 0xffff0000, v57
	v_pk_add_f32 v[40:41], v[40:41], v[56:57]
	v_pk_add_f32 v[38:39], v[38:39], v[54:55]
	s_nop 0
	v_cvt_pk_bf16_f32 v54, v38, v39
	v_cvt_pk_bf16_f32 v55, v40, v41
	v_mul_f32_e32 v39, v39, v39
	v_fmac_f32_e32 v39, v38, v38
	v_fmac_f32_e32 v39, v40, v40
	v_fmac_f32_e32 v39, v41, v41
	v_add_f32_e32 v42, v42, v39
	global_store_dwordx2 v[52:53], v[54:55], off offset:256
	s_waitcnt vmcnt(31)
	v_mov_b64_e32 v[56:57], v[238:239]
	v_lshlrev_b32_e32 v38, 16, v56
	v_and_b32_e32 v39, 0xffff0000, v56
	v_pk_add_f32 v[38:39], v[34:35], v[38:39]
	v_lshlrev_b32_e32 v40, 16, v57
	v_and_b32_e32 v41, 0xffff0000, v57
	v_mul_f32_e32 v34, v39, v39
	v_pk_add_f32 v[36:37], v[36:37], v[40:41]
	v_fmac_f32_e32 v34, v38, v38
	v_fmac_f32_e32 v34, v36, v36
	v_fmac_f32_e32 v34, v37, v37
	v_add_f32_e32 v34, v42, v34
	ds_bpermute_b32 v35, v0, v34
	v_cvt_pk_bf16_f32 v38, v38, v39
	v_cvt_pk_bf16_f32 v39, v36, v37
	global_store_dwordx2 v[52:53], v[38:39], off offset:288
	s_waitcnt lgkmcnt(0)
	v_add_f32_e32 v34, v34, v35
	ds_bpermute_b32 v35, v116, v34
	s_and_saveexec_b64 s[8:9], vcc
	s_cbranch_execz .LBB0_982
	s_waitcnt lgkmcnt(0)
	v_add_f32_e32 v34, v34, v35
	v_lshl_add_u32 v35, v50, 4, s10
	ds_write_b32 v35, v34
; __device__ __forceinline__ float bflo(unsigned w) { return __uint_as_float(w << 16); }
; __device__ __forceinline__ float bfhi(unsigned w) { return __uint_as_float(w & 0xffff0000u); }
; template <int MODE, bool PRE = false, bool NEXT = false> ...
;     ...
;       } else if constexpr (MODE == EP_RES) {
;         float* orow = (float*)e.out + (long)row * e.ldo + cbase;
;         const float* arow = (const float*)e.aux + (long)row * e.ldaux + cbase;
;         const u16* brow = (const u16*)e.aux + (long)row * e.ldaux + cbase;
;         u16* xrow = e.xb + (long)row * 1024 + cbase;
;         float part = 0.f;
; #pragma unroll
;         for (int bj = 0; bj < 2; ++bj)
; #pragma unroll
;           for (int n = 0; n < 2; ++n) {
;             f32x4 a;
;             if (e.auxbf) { const u32x2 w = *reinterpret_cast<const u32x2*>(brow + bj * 128 + n * 16); a = f32x4{bflo(w[0]), bfhi(w[0]), bflo(w[1]), bfhi(w[1])}; }
;             else a = *reinterpret_cast<const f32x4*>(arow + bj * 128 + n * 16);
;             a += acc[ai][bj][m][n];
;             if (e.out) *reinterpret_cast<f32x4*>(orow + bj * 128 + n * 16) = a;
;             if (e.xb) {
;               u32x2 w = {cvtpk(a[0], a[1]), cvtpk(a[2], a[3])};
;               *reinterpret_cast<u32x2*>(xrow + bj * 128 + n * 16) = w;
;               part += a[0] * a[0] + a[1] * a[1] + a[2] * a[2] + a[3] * a[3];
;             }
;           }
;         if (e.xb) {
;           part += __int_as_float(__builtin_amdgcn_ds_bpermute((lane ^ 16) << 2, __float_as_int(part)));
;           part += __int_as_float(__builtin_amdgcn_ds_bpermute((lane ^ 32) << 2, __float_as_int(part)));
;           if (fq == 0) reinterpret_cast<float*>(g_lds)[row * 4 + wc] = part;
;         }
.LBB0_982:
	s_or_b64 exec, exec, s[8:9]
	v_add_u32_e32 v34, 0xa0, v132
	s_waitcnt lgkmcnt(0)
	v_ashrrev_i32_e32 v35, 31, v34
	v_lshlrev_b64 v[36:37], 11, v[34:35]
	v_lshl_add_u64 v[36:37], v[134:135], 0, v[36:37]
	s_waitcnt vmcnt(31)
	v_mov_b64_e32 v[38:39], v[240:241]
	v_lshlrev_b32_e32 v40, 16, v38
	v_and_b32_e32 v41, 0xffff0000, v38
	v_lshlrev_b32_e32 v38, 16, v39
	v_and_b32_e32 v39, 0xffff0000, v39
	v_pk_add_f32 v[32:33], v[32:33], v[38:39]
	v_pk_add_f32 v[30:31], v[30:31], v[40:41]
	s_nop 0
	v_cvt_pk_bf16_f32 v38, v30, v31
	v_cvt_pk_bf16_f32 v39, v32, v33
	v_mul_f32_e32 v31, v31, v31
	global_store_dwordx2 v[36:37], v[38:39], off
	v_fmac_f32_e32 v31, v30, v30
	v_fmac_f32_e32 v31, v32, v32
	v_fmac_f32_e32 v31, v33, v33
	s_waitcnt vmcnt(31)
	v_mov_b64_e32 v[40:41], v[242:243]
	v_lshlrev_b32_e32 v38, 16, v40
	v_and_b32_e32 v39, 0xffff0000, v40
	v_lshlrev_b32_e32 v40, 16, v41
	v_and_b32_e32 v41, 0xffff0000, v41
	v_pk_add_f32 v[28:29], v[28:29], v[40:41]
	v_pk_add_f32 v[26:27], v[26:27], v[38:39]
	s_nop 0
	v_cvt_pk_bf16_f32 v38, v26, v27
	v_cvt_pk_bf16_f32 v39, v28, v29
	v_mul_f32_e32 v27, v27, v27
	global_store_dwordx2 v[36:37], v[38:39], off offset:32
	v_fmac_f32_e32 v27, v26, v26
	v_fmac_f32_e32 v27, v28, v28
	v_fmac_f32_e32 v27, v29, v29
	v_add_f32_e32 v26, v31, v27
	s_waitcnt vmcnt(31)
	v_mov_b64_e32 v[40:41], v[244:245]
	v_lshlrev_b32_e32 v38, 16, v40
	v_and_b32_e32 v39, 0xffff0000, v40
	v_lshlrev_b32_e32 v40, 16, v41
	v_and_b32_e32 v41, 0xffff0000, v41
	v_pk_add_f32 v[24:25], v[24:25], v[40:41]
	v_pk_add_f32 v[22:23], v[22:23], v[38:39]
	s_nop 0
	v_cvt_pk_bf16_f32 v38, v22, v23
	v_cvt_pk_bf16_f32 v39, v24, v25
	v_mul_f32_e32 v23, v23, v23
	v_fmac_f32_e32 v23, v22, v22
	v_fmac_f32_e32 v23, v24, v24
	v_fmac_f32_e32 v23, v25, v25
	v_add_f32_e32 v26, v26, v23
	global_store_dwordx2 v[36:37], v[38:39], off offset:256
	s_waitcnt vmcnt(31)
	v_mov_b64_e32 v[40:41], v[246:247]
	v_lshlrev_b32_e32 v22, 16, v40
	v_and_b32_e32 v23, 0xffff0000, v40
	v_pk_add_f32 v[22:23], v[18:19], v[22:23]
	v_lshlrev_b32_e32 v24, 16, v41
	v_and_b32_e32 v25, 0xffff0000, v41
	v_mul_f32_e32 v18, v23, v23
	v_pk_add_f32 v[20:21], v[20:21], v[24:25]
	v_fmac_f32_e32 v18, v22, v22
	v_fmac_f32_e32 v18, v20, v20
	v_fmac_f32_e32 v18, v21, v21
	v_add_f32_e32 v18, v26, v18
	ds_bpermute_b32 v19, v0, v18
	v_cvt_pk_bf16_f32 v22, v22, v23
	v_cvt_pk_bf16_f32 v23, v20, v21
	global_store_dwordx2 v[36:37], v[22:23], off offset:288
	s_waitcnt lgkmcnt(0)
	v_add_f32_e32 v18, v18, v19
	ds_bpermute_b32 v19, v116, v18
	s_and_saveexec_b64 s[8:9], vcc
	s_cbranch_execz .LBB0_984
	s_waitcnt lgkmcnt(0)
	v_add_f32_e32 v18, v18, v19
	v_lshl_add_u32 v19, v34, 4, s10
	ds_write_b32 v19, v18
.LBB0_984:
	s_or_b64 exec, exec, s[8:9]
	v_add_u32_e32 v18, 0xb0, v132
	s_waitcnt lgkmcnt(0)
	v_ashrrev_i32_e32 v19, 31, v18
	v_lshlrev_b64 v[20:21], 11, v[18:19]
	v_lshl_add_u64 v[20:21], v[134:135], 0, v[20:21]
	s_waitcnt vmcnt(31)
	v_mov_b64_e32 v[22:23], v[248:249]
	v_lshlrev_b32_e32 v24, 16, v22
	v_and_b32_e32 v25, 0xffff0000, v22
	v_lshlrev_b32_e32 v22, 16, v23
	v_and_b32_e32 v23, 0xffff0000, v23
	v_pk_add_f32 v[16:17], v[16:17], v[22:23]
	v_pk_add_f32 v[14:15], v[14:15], v[24:25]
	s_nop 0
	v_cvt_pk_bf16_f32 v22, v14, v15
	v_cvt_pk_bf16_f32 v23, v16, v17
	v_mul_f32_e32 v15, v15, v15
	global_store_dwordx2 v[20:21], v[22:23], off
	v_fmac_f32_e32 v15, v14, v14
	v_fmac_f32_e32 v15, v16, v16
	v_fmac_f32_e32 v15, v17, v17
	s_waitcnt vmcnt(31)
	v_mov_b64_e32 v[24:25], v[250:251]
	v_lshlrev_b32_e32 v22, 16, v24
	v_and_b32_e32 v23, 0xffff0000, v24
	v_lshlrev_b32_e32 v24, 16, v25
	v_and_b32_e32 v25, 0xffff0000, v25
	v_pk_add_f32 v[12:13], v[12:13], v[24:25]
	v_pk_add_f32 v[10:11], v[10:11], v[22:23]
	s_nop 0
	v_cvt_pk_bf16_f32 v22, v10, v11
	v_cvt_pk_bf16_f32 v23, v12, v13
	v_mul_f32_e32 v11, v11, v11
	global_store_dwordx2 v[20:21], v[22:23], off offset:32
	v_fmac_f32_e32 v11, v10, v10
	v_fmac_f32_e32 v11, v12, v12
	v_fmac_f32_e32 v11, v13, v13
	v_add_f32_e32 v10, v15, v11
	s_waitcnt vmcnt(31)
	v_mov_b64_e32 v[24:25], v[182:183]
	v_lshlrev_b32_e32 v22, 16, v24
	v_and_b32_e32 v23, 0xffff0000, v24
	v_lshlrev_b32_e32 v24, 16, v25
	v_and_b32_e32 v25, 0xffff0000, v25
	v_pk_add_f32 v[8:9], v[8:9], v[24:25]
	v_pk_add_f32 v[6:7], v[6:7], v[22:23]
	s_nop 0
	v_cvt_pk_bf16_f32 v22, v6, v7
	v_cvt_pk_bf16_f32 v23, v8, v9
	v_mul_f32_e32 v7, v7, v7
	v_fmac_f32_e32 v7, v6, v6
	v_fmac_f32_e32 v7, v8, v8
	v_fmac_f32_e32 v7, v9, v9
	v_add_f32_e32 v10, v10, v7
	global_store_dwordx2 v[20:21], v[22:23], off offset:256
	s_waitcnt vmcnt(31)
	v_mov_b64_e32 v[24:25], v[184:185]
	v_lshlrev_b32_e32 v6, 16, v24
	v_and_b32_e32 v7, 0xffff0000, v24
	v_pk_add_f32 v[6:7], v[2:3], v[6:7]
	v_lshlrev_b32_e32 v8, 16, v25
	v_and_b32_e32 v9, 0xffff0000, v25
	v_mul_f32_e32 v2, v7, v7
	v_pk_add_f32 v[4:5], v[4:5], v[8:9]
	v_fmac_f32_e32 v2, v6, v6
	v_fmac_f32_e32 v2, v4, v4
	v_fmac_f32_e32 v2, v5, v5
	v_add_f32_e32 v2, v10, v2
	ds_bpermute_b32 v0, v0, v2
	v_cvt_pk_bf16_f32 v6, v6, v7
	v_cvt_pk_bf16_f32 v7, v4, v5
	global_store_dwordx2 v[20:21], v[6:7], off offset:288
	s_waitcnt lgkmcnt(0)
	v_add_f32_e32 v0, v2, v0
	ds_bpermute_b32 v2, v116, v0
	s_and_saveexec_b64 s[8:9], vcc
	s_cbranch_execz .LBB0_986
	s_waitcnt lgkmcnt(0)
	v_add_f32_e32 v0, v0, v2
	v_lshl_add_u32 v2, v18, 4, s10
	ds_write_b32 v2, v0
